# attention queue: FoX units of a round handed out before its NSA units (one s_xor on the unit index), on top of rope batching
# speedup vs baseline: 1.0007x; 1.0007x over previous
.LBB0_815:
	s_or_b64 exec, exec, s[12:13]
	v_mov_b32_e32 v0, s97
	s_waitcnt lgkmcnt(0)
	s_barrier
	ds_read_b32 v0, v0
	s_movk_i32 s0, 0x200
	s_mov_b64 s[12:13], -1
	s_waitcnt lgkmcnt(0)
	s_barrier
	v_cmp_gt_u32_e32 vcc, s0, v0
	v_readfirstlane_b32 s62, v0
	s_cbranch_vccz .LBB0_864
	s_lshr_b32 s59, s62, 5
	s_and_b32 s60, s62, 31
	s_xor_b32 s60, s60, 16
	s_cmp_gt_u32 s60, 15
	v_lshlrev_b32_e32 v168, 1, v188
	s_cbranch_scc0 .LBB0_867
	s_add_i32 s0, s60, -16
	s_lshl_b32 s2, s59, 2
	s_and_b32 s2, s2, 12
	s_lshr_b32 s0, s0, 2
	s_add_i32 s20, s2, s0
	s_and_b32 s0, s59, 12
	s_xor_b32 s2, s0, 15
	s_and_b32 s22, s62, 3
	v_readfirstlane_b32 s0, v187
	s_sub_i32 s16, s2, s22
	s_ashr_i32 s0, s0, 1
	s_lshl_b32 s12, s16, 8
	s_and_b32 s23, s0, 0xffffffe0
	s_add_i32 s23, s23, s12
	v_or_b32_e32 v172, s23, v193
	v_readlane_b32 s18, v252, 12
	s_lshl_b32 s0, s20, 12
	s_waitcnt vmcnt(10)
	v_ashrrev_i32_e32 v173, 31, v172
	v_readlane_b32 s19, v252, 13
	v_lshl_add_u64 v[170:171], v[172:173], 0, s[0:1]
	s_mul_i32 s24, s20, 0x2600000
	v_mov_b64_e32 v[0:1], s[18:19]
	v_mad_u64_u32 v[0:1], s[12:13], v170, s70, v[0:1]
	v_mad_i32_i24 v1, v171, s70, v1
	s_lshl_b32 s12, s58, 7
	s_mov_b32 s13, s1
	v_lshl_add_u64 v[0:1], v[0:1], 0, s[12:13]
	s_lshl_b32 s13, s16, 2
	s_mul_hi_u32 s25, s0, 0x2600
	s_add_u32 s0, s18, s24
	s_addc_u32 s17, s19, s25
	s_add_u32 s16, s0, s12
	s_addc_u32 s17, s17, 0
	s_add_u32 s18, s16, 0x1200
	s_addc_u32 s19, s17, 0
	s_lshl_b32 s0, s20, 15
	s_lshl_b32 s20, s58, 12
	s_or_b32 s0, s0, s20
	s_lshl_b64 s[20:21], s[0:1], 2
	v_readlane_b32 s0, v252, 16
	s_add_u32 s52, s0, s20
	v_readlane_b32 s0, v252, 17
	s_addc_u32 s53, s0, s21
	s_or_b32 s66, s13, 3
	s_mul_i32 s0, s66, 0x4c000
	s_lshl_b32 s26, s0, 1
	s_waitcnt vmcnt(8)
	v_mov_b32_e32 v169, v2
	s_add_u32 s20, s16, s26
	v_lshl_add_u64 v[0:1], v[0:1], 0, v[168:169]
	s_addc_u32 s21, s17, 0
	v_lshlrev_b64 v[4:5], 1, v[190:191]
	global_load_dwordx4 v[112:115], v[0:1], off offset:2560
	global_load_dwordx4 v[116:119], v[0:1], off offset:2592
	global_load_dwordx4 v[120:123], v[0:1], off offset:2624
	global_load_dwordx4 v[124:127], v[0:1], off offset:2656
	v_lshl_add_u64 v[0:1], s[20:21], 0, v[4:5]
	s_add_u32 s20, s18, s26
	s_addc_u32 s21, s19, 0
	v_lshl_add_u64 v[6:7], s[20:21], 0, v[4:5]
	global_load_dwordx4 v[132:135], v[0:1], off offset:3584
	global_load_dwordx4 v[136:139], v[6:7], off
	v_mov_b32_e32 v169, 0
	v_mov_b32_e32 v173, 0
	s_and_saveexec_b64 s[20:21], s[8:9]
	s_cbranch_execz .LBB0_819
	v_lshl_add_u32 v0, s66, 6, v187
	v_ashrrev_i32_e32 v1, 31, v0
	v_lshl_add_u64 v[0:1], v[0:1], 2, s[52:53]
	global_load_dword v173, v[0:1], off
